# stack + MoBA softmax: O rescale skipped when no row max rises by more than 8 (exact, alpha=1); fp8 x16 pre-scale folded into 1/l
# speedup vs baseline: 1.0029x; 1.0029x over previous
.LBB0_395:
	s_nop 0
	v_max3_f32 v244, v48, s38, v49
	v_max3_f32 v244, v244, v50, v51
	v_max3_f32 v244, v244, v52, v53
	v_max3_f32 v244, v244, v54, v55
	v_max3_f32 v244, v244, v56, v57
	v_max3_f32 v244, v244, v58, v59
	v_max3_f32 v244, v244, v60, v61
	v_max3_f32 v244, v244, v62, v63
	v_max3_f32 v244, v244, v32, v33
	v_max3_f32 v244, v244, v34, v35
	v_max3_f32 v244, v244, v36, v37
	v_max3_f32 v244, v244, v38, v39
	v_max3_f32 v244, v244, v40, v41
	v_max3_f32 v244, v244, v42, v43
	v_max3_f32 v244, v244, v44, v45
	v_max3_f32 v244, v244, v46, v47
	ds_bpermute_b32 v245, v238, v244
	s_waitcnt lgkmcnt(0)
	v_max3_f32 v245, v197, v244, v245
	v_sub_f32_e32 v244, v245, v197
	v_cmp_lt_f32_e32 vcc, 0x41000000, v244
	s_cmp_lg_u64 vcc, 0
	s_cbranch_scc1 .Lp3lz_full2
	v_mov_b32_e32 v245, v197
.Lp3lz_full2:
	v_sub_f32_e32 v197, v197, v245
	v_sub_f32_e32 v48, v48, v245
	v_exp_f32_e32 v244, v197
	v_exp_f32_e32 v197, v48
	v_sub_f32_e32 v48, v49, v245
	v_exp_f32_e32 v246, v48
	v_sub_f32_e32 v48, v50, v245
	v_exp_f32_e32 v247, v48
	v_sub_f32_e32 v48, v51, v245
	v_exp_f32_e32 v248, v48
	v_sub_f32_e32 v48, v52, v245
	v_exp_f32_e32 v52, v48
	v_sub_f32_e32 v48, v53, v245
	v_exp_f32_e32 v53, v48
	v_sub_f32_e32 v48, v54, v245
	v_exp_f32_e32 v54, v48
	v_sub_f32_e32 v48, v55, v245
	v_exp_f32_e32 v55, v48
	v_sub_f32_e32 v48, v56, v245
	v_exp_f32_e32 v56, v48
	v_sub_f32_e32 v48, v57, v245
	v_exp_f32_e32 v57, v48
	v_sub_f32_e32 v48, v58, v245
	v_exp_f32_e32 v58, v48
	v_sub_f32_e32 v48, v59, v245
	v_exp_f32_e32 v59, v48
	v_sub_f32_e32 v48, v60, v245
	v_exp_f32_e32 v60, v48
	v_sub_f32_e32 v48, v61, v245
	v_exp_f32_e32 v61, v48
	v_sub_f32_e32 v48, v62, v245
	v_exp_f32_e32 v62, v48
	v_sub_f32_e32 v48, v63, v245
	v_exp_f32_e32 v63, v48
	v_cvt_pk_bf16_f32 v48, v197, v246
	v_cvt_pk_bf16_f32 v49, v247, v248
	v_cvt_pk_bf16_f32 v50, v52, v53
	v_cvt_pk_bf16_f32 v51, v54, v55
	s_cbranch_scc0 .Lp3lz_skip2
	v_pk_mul_f32 v[14:15], v[14:15], v[244:245] op_sel_hi:[1,0]
	v_pk_mul_f32 v[12:13], v[12:13], v[244:245] op_sel_hi:[1,0]
	v_pk_mul_f32 v[10:11], v[10:11], v[244:245] op_sel_hi:[1,0]
	v_pk_mul_f32 v[8:9], v[8:9], v[244:245] op_sel_hi:[1,0]
	v_pk_mul_f32 v[6:7], v[6:7], v[244:245] op_sel_hi:[1,0]
	v_pk_mul_f32 v[4:5], v[4:5], v[244:245] op_sel_hi:[1,0]
	v_pk_mul_f32 v[2:3], v[2:3], v[244:245] op_sel_hi:[1,0]
	v_pk_mul_f32 v[0:1], v[0:1], v[244:245] op_sel_hi:[1,0]
	v_pk_mul_f32 v[30:31], v[30:31], v[244:245] op_sel_hi:[1,0]
	v_pk_mul_f32 v[28:29], v[28:29], v[244:245] op_sel_hi:[1,0]
	v_pk_mul_f32 v[26:27], v[26:27], v[244:245] op_sel_hi:[1,0]
	v_pk_mul_f32 v[24:25], v[24:25], v[244:245] op_sel_hi:[1,0]
	v_pk_mul_f32 v[22:23], v[22:23], v[244:245] op_sel_hi:[1,0]
	v_pk_mul_f32 v[20:21], v[20:21], v[244:245] op_sel_hi:[1,0]
	v_pk_mul_f32 v[18:19], v[18:19], v[244:245] op_sel_hi:[1,0]
	v_pk_mul_f32 v[16:17], v[16:17], v[244:245] op_sel_hi:[1,0]
.Lp3lz_skip2:
	s_nop 1
	v_mfma_f32_32x32x16_bf16 v[0:15], v[156:159], v[48:51], v[0:15]
	v_fmac_f32_e32 v197, v162, v244
	v_sub_f32_e32 v32, v32, v245
	v_mfma_f32_32x32x16_bf16 v[16:31], v[152:155], v[48:51], v[16:31]
	v_cvt_pk_bf16_f32 v48, v56, v57
	v_cvt_pk_bf16_f32 v49, v58, v59
	v_cvt_pk_bf16_f32 v50, v60, v61
	v_cvt_pk_bf16_f32 v51, v62, v63
	s_nop 1
	v_mfma_f32_32x32x16_bf16 v[0:15], v[144:147], v[48:51], v[0:15]
	v_mfma_f32_32x32x16_bf16 v[16:31], v[148:151], v[48:51], v[16:31]
	v_add_f32_e32 v48, v246, v197
	v_exp_f32_e32 v49, v32
	v_sub_f32_e32 v32, v33, v245
	v_add_f32_e32 v48, v247, v48
	v_exp_f32_e32 v50, v32
	v_sub_f32_e32 v32, v34, v245
	v_add_f32_e32 v48, v248, v48
	v_exp_f32_e32 v51, v32
	v_sub_f32_e32 v32, v35, v245
	v_add_f32_e32 v48, v52, v48
	v_exp_f32_e32 v52, v32
	v_sub_f32_e32 v32, v36, v245
	v_exp_f32_e32 v36, v32
	v_sub_f32_e32 v32, v37, v245
	v_exp_f32_e32 v37, v32
	v_sub_f32_e32 v32, v38, v245
	v_exp_f32_e32 v38, v32
	v_sub_f32_e32 v32, v39, v245
	v_exp_f32_e32 v39, v32
	v_sub_f32_e32 v32, v40, v245
	v_exp_f32_e32 v40, v32
	v_sub_f32_e32 v32, v41, v245
	v_exp_f32_e32 v41, v32
	v_sub_f32_e32 v32, v42, v245
	v_exp_f32_e32 v42, v32
	v_sub_f32_e32 v32, v43, v245
	v_exp_f32_e32 v43, v32
	v_sub_f32_e32 v32, v44, v245
	v_exp_f32_e32 v44, v32
	v_sub_f32_e32 v32, v45, v245
	v_add_f32_e32 v48, v53, v48
	v_exp_f32_e32 v45, v32
	v_sub_f32_e32 v32, v46, v245
	v_add_f32_e32 v48, v54, v48
	v_exp_f32_e32 v46, v32
	v_sub_f32_e32 v32, v47, v245
	v_add_f32_e32 v48, v55, v48
	v_exp_f32_e32 v47, v32
	v_cvt_pk_bf16_f32 v32, v49, v50
	v_cvt_pk_bf16_f32 v33, v51, v52
	v_cvt_pk_bf16_f32 v34, v36, v37
	v_cvt_pk_bf16_f32 v35, v38, v39
	v_add_f32_e32 v48, v56, v48
	v_add_f32_e32 v48, v57, v48
	v_mfma_f32_32x32x16_bf16 v[0:15], v[140:143], v[32:35], v[0:15]
	v_add_f32_e32 v48, v58, v48
	v_add_f32_e32 v48, v59, v48
	v_add_f32_e32 v48, v60, v48
	v_add_f32_e32 v48, v61, v48
	v_add_f32_e32 v48, v62, v48
	v_add_f32_e32 v48, v63, v48
	v_mov_b32_e32 v197, v245
	v_mfma_f32_32x32x16_bf16 v[16:31], v[136:139], v[32:35], v[16:31]
	v_cvt_pk_bf16_f32 v32, v40, v41
	v_cvt_pk_bf16_f32 v33, v42, v43
	v_cvt_pk_bf16_f32 v34, v44, v45
	v_cvt_pk_bf16_f32 v35, v46, v47
	s_nop 1
	v_mfma_f32_32x32x16_bf16 v[0:15], v[132:135], v[32:35], v[0:15]
	v_mfma_f32_32x32x16_bf16 v[16:31], v[128:131], v[32:35], v[16:31]
	v_add_f32_e32 v32, v49, v48
	v_add_f32_e32 v32, v50, v32
	v_add_f32_e32 v32, v51, v32
	v_add_f32_e32 v32, v52, v32
	v_add_f32_e32 v32, v36, v32
	v_add_f32_e32 v32, v37, v32
	v_add_f32_e32 v32, v38, v32
	v_add_f32_e32 v32, v39, v32
	v_add_f32_e32 v32, v40, v32
	v_add_f32_e32 v32, v41, v32
	v_add_f32_e32 v32, v42, v32
	v_add_f32_e32 v32, v43, v32
	v_add_f32_e32 v32, v44, v32
	v_add_f32_e32 v32, v45, v32
	v_add_f32_e32 v32, v46, v32
	v_add_f32_e32 v162, v47, v32
	s_cmp_lt_u32 s58, 4
	s_cbranch_scc0 .LBB0_398

.Lp3lz_full3:
	v_sub_f32_e32 v197, v197, v245
	v_sub_f32_e32 v48, v48, v245
	v_exp_f32_e32 v244, v197
	v_exp_f32_e32 v197, v48
	v_sub_f32_e32 v48, v49, v245
	v_exp_f32_e32 v246, v48
	v_sub_f32_e32 v48, v50, v245
	v_exp_f32_e32 v247, v48
	v_sub_f32_e32 v48, v51, v245
	v_exp_f32_e32 v248, v48
	v_sub_f32_e32 v48, v52, v245
	v_exp_f32_e32 v52, v48
	v_sub_f32_e32 v48, v53, v245
	v_exp_f32_e32 v53, v48
	v_sub_f32_e32 v48, v54, v245
	v_exp_f32_e32 v54, v48
	v_sub_f32_e32 v48, v55, v245
	v_exp_f32_e32 v55, v48
	v_sub_f32_e32 v48, v56, v245
	v_exp_f32_e32 v56, v48
	v_sub_f32_e32 v48, v57, v245
	v_exp_f32_e32 v57, v48
	v_sub_f32_e32 v48, v58, v245
	v_exp_f32_e32 v58, v48
	v_sub_f32_e32 v48, v59, v245
	v_exp_f32_e32 v59, v48
	v_sub_f32_e32 v48, v60, v245
	v_exp_f32_e32 v60, v48
	v_sub_f32_e32 v48, v61, v245
	v_exp_f32_e32 v61, v48
	v_sub_f32_e32 v48, v62, v245
	v_exp_f32_e32 v62, v48
	v_sub_f32_e32 v48, v63, v245
	s_cbranch_scc0 .Lp3lz_skip3
	v_pk_mul_f32 v[0:1], v[0:1], v[244:245] op_sel_hi:[1,0]
	v_pk_mul_f32 v[16:17], v[16:17], v[244:245] op_sel_hi:[1,0]
	v_pk_mul_f32 v[2:3], v[2:3], v[244:245] op_sel_hi:[1,0]
	v_pk_mul_f32 v[18:19], v[18:19], v[244:245] op_sel_hi:[1,0]
	v_pk_mul_f32 v[4:5], v[4:5], v[244:245] op_sel_hi:[1,0]
	v_pk_mul_f32 v[20:21], v[20:21], v[244:245] op_sel_hi:[1,0]
	v_pk_mul_f32 v[6:7], v[6:7], v[244:245] op_sel_hi:[1,0]
	v_pk_mul_f32 v[22:23], v[22:23], v[244:245] op_sel_hi:[1,0]
	v_pk_mul_f32 v[8:9], v[8:9], v[244:245] op_sel_hi:[1,0]
	v_pk_mul_f32 v[24:25], v[24:25], v[244:245] op_sel_hi:[1,0]
	v_pk_mul_f32 v[10:11], v[10:11], v[244:245] op_sel_hi:[1,0]
	v_pk_mul_f32 v[26:27], v[26:27], v[244:245] op_sel_hi:[1,0]
	v_pk_mul_f32 v[12:13], v[12:13], v[244:245] op_sel_hi:[1,0]
	v_pk_mul_f32 v[28:29], v[28:29], v[244:245] op_sel_hi:[1,0]
	v_pk_mul_f32 v[14:15], v[14:15], v[244:245] op_sel_hi:[1,0]
	v_pk_mul_f32 v[30:31], v[30:31], v[244:245] op_sel_hi:[1,0]
.Lp3lz_skip3:
	v_exp_f32_e32 v63, v48
	v_cvt_pk_bf16_f32 v48, v197, v246
	v_cvt_pk_bf16_f32 v49, v247, v248
	v_cvt_pk_bf16_f32 v50, v52, v53
	v_cvt_pk_bf16_f32 v51, v54, v55
	v_fmac_f32_e32 v197, v162, v244
	v_sub_f32_e32 v32, v32, v245
	v_mfma_f32_32x32x16_bf16 v[0:15], v[156:159], v[48:51], v[0:15]
	v_mfma_f32_32x32x16_bf16 v[16:31], v[152:155], v[48:51], v[16:31]
	v_cvt_pk_bf16_f32 v48, v56, v57
	v_cvt_pk_bf16_f32 v49, v58, v59
	v_cvt_pk_bf16_f32 v50, v60, v61
	v_cvt_pk_bf16_f32 v51, v62, v63
	s_nop 1
	v_mfma_f32_32x32x16_bf16 v[0:15], v[144:147], v[48:51], v[0:15]
	v_mfma_f32_32x32x16_bf16 v[16:31], v[148:151], v[48:51], v[16:31]
	v_add_f32_e32 v48, v246, v197
	v_exp_f32_e32 v49, v32
	v_sub_f32_e32 v32, v33, v245
	v_add_f32_e32 v48, v247, v48
	v_exp_f32_e32 v50, v32
	v_sub_f32_e32 v32, v34, v245
	v_add_f32_e32 v48, v248, v48
	v_exp_f32_e32 v51, v32
	v_sub_f32_e32 v32, v35, v245
	v_add_f32_e32 v48, v52, v48
	v_exp_f32_e32 v52, v32
	v_sub_f32_e32 v32, v36, v245
	v_exp_f32_e32 v36, v32
	v_sub_f32_e32 v32, v37, v245
	v_exp_f32_e32 v37, v32
	v_sub_f32_e32 v32, v38, v245
	v_exp_f32_e32 v38, v32
	v_sub_f32_e32 v32, v39, v245
	v_exp_f32_e32 v39, v32
	v_sub_f32_e32 v32, v40, v245
	v_exp_f32_e32 v40, v32
	v_sub_f32_e32 v32, v41, v245
	v_exp_f32_e32 v41, v32
	v_sub_f32_e32 v32, v42, v245
	v_exp_f32_e32 v42, v32
	v_sub_f32_e32 v32, v43, v245
	v_exp_f32_e32 v43, v32
	v_sub_f32_e32 v32, v44, v245
	v_exp_f32_e32 v44, v32
	v_sub_f32_e32 v32, v45, v245
	v_add_f32_e32 v48, v53, v48
	v_exp_f32_e32 v45, v32
	v_sub_f32_e32 v32, v46, v245
	v_add_f32_e32 v48, v54, v48
	v_exp_f32_e32 v46, v32
	v_sub_f32_e32 v32, v47, v245
	v_add_f32_e32 v48, v55, v48
	v_exp_f32_e32 v47, v32
	v_cvt_pk_bf16_f32 v32, v49, v50
	v_cvt_pk_bf16_f32 v33, v51, v52
	v_cvt_pk_bf16_f32 v34, v36, v37
	v_cvt_pk_bf16_f32 v35, v38, v39
	v_add_f32_e32 v48, v56, v48
	v_add_f32_e32 v48, v57, v48
	v_mfma_f32_32x32x16_bf16 v[0:15], v[140:143], v[32:35], v[0:15]
	v_add_f32_e32 v48, v58, v48
	v_add_f32_e32 v48, v59, v48
	v_add_f32_e32 v48, v60, v48
	v_add_f32_e32 v48, v61, v48
	v_add_f32_e32 v48, v62, v48
	v_add_f32_e32 v48, v63, v48
	v_mov_b32_e32 v197, v245
	v_mfma_f32_32x32x16_bf16 v[16:31], v[136:139], v[32:35], v[16:31]
	v_cvt_pk_bf16_f32 v32, v40, v41
	v_cvt_pk_bf16_f32 v33, v42, v43
	v_cvt_pk_bf16_f32 v34, v44, v45
	v_cvt_pk_bf16_f32 v35, v46, v47
	s_nop 1
	v_mfma_f32_32x32x16_bf16 v[0:15], v[132:135], v[32:35], v[0:15]
	v_mfma_f32_32x32x16_bf16 v[16:31], v[128:131], v[32:35], v[16:31]
	v_add_f32_e32 v32, v49, v48
	v_add_f32_e32 v32, v50, v32
	v_add_f32_e32 v32, v51, v32
	v_add_f32_e32 v32, v52, v32
	v_add_f32_e32 v32, v36, v32
	v_add_f32_e32 v32, v37, v32
	v_add_f32_e32 v32, v38, v32
	v_add_f32_e32 v32, v39, v32
	v_add_f32_e32 v32, v40, v32
	v_add_f32_e32 v32, v41, v32
	v_add_f32_e32 v32, v42, v32
	v_add_f32_e32 v32, v43, v32
	v_add_f32_e32 v32, v44, v32
	v_add_f32_e32 v32, v45, v32
	v_add_f32_e32 v32, v46, v32
	v_add_f32_e32 v162, v47, v32
	s_cmp_lt_u32 s58, 6
	s_cbranch_scc1 .LBB0_404

.LBB0_403:
	s_nop 0
	v_max3_f32 v96, v48, s38, v49
	v_max3_f32 v96, v96, v50, v51
	v_max3_f32 v96, v96, v52, v53
	v_max3_f32 v96, v96, v54, v55
	v_max3_f32 v96, v96, v56, v57
	v_max3_f32 v96, v96, v58, v59
	v_max3_f32 v96, v96, v60, v61
	v_max3_f32 v96, v96, v62, v63
	s_nop 1
	v_max3_f32 v96, v96, v32, v33
	v_max3_f32 v96, v96, v34, v35
	v_max3_f32 v96, v96, v36, v37
	v_max3_f32 v96, v96, v38, v39
	v_max3_f32 v96, v96, v40, v41
	v_max3_f32 v96, v96, v42, v43
	v_max3_f32 v96, v96, v44, v45
	v_max3_f32 v96, v96, v46, v47
	ds_bpermute_b32 v97, v238, v96
	s_waitcnt lgkmcnt(0)
	v_max3_f32 v97, v197, v96, v97
	v_sub_f32_e32 v96, v97, v197
	v_cmp_lt_f32_e32 vcc, 0x41000000, v96
	s_cmp_lg_u64 vcc, 0
	s_cbranch_scc1 .Lp3lz_full4
	v_mov_b32_e32 v97, v197
.Lp3lz_full4:
	v_sub_f32_e32 v48, v48, v97
	v_exp_f32_e32 v98, v48
	v_sub_f32_e32 v48, v49, v97
	v_exp_f32_e32 v99, v48
	v_sub_f32_e32 v48, v50, v97
	v_exp_f32_e32 v148, v48
	v_sub_f32_e32 v48, v51, v97
	v_exp_f32_e32 v149, v48
	v_sub_f32_e32 v48, v52, v97
	v_exp_f32_e32 v52, v48
	v_sub_f32_e32 v48, v53, v97
	v_exp_f32_e32 v53, v48
	v_sub_f32_e32 v48, v54, v97
	v_exp_f32_e32 v54, v48
	v_sub_f32_e32 v48, v55, v97
	v_exp_f32_e32 v55, v48
	v_sub_f32_e32 v48, v56, v97
	v_exp_f32_e32 v56, v48
	v_sub_f32_e32 v48, v57, v97
	v_exp_f32_e32 v57, v48
	v_sub_f32_e32 v48, v58, v97
	v_sub_f32_e32 v96, v197, v97
	v_exp_f32_e32 v58, v48
	v_sub_f32_e32 v48, v59, v97
	v_exp_f32_e32 v96, v96
	v_exp_f32_e32 v59, v48
	v_sub_f32_e32 v48, v60, v97
	v_exp_f32_e32 v60, v48
	v_sub_f32_e32 v48, v61, v97
	v_exp_f32_e32 v61, v48
	v_sub_f32_e32 v48, v62, v97
	v_exp_f32_e32 v62, v48
	v_sub_f32_e32 v48, v63, v97
	s_cbranch_scc0 .Lp3lz_skip4
	v_pk_mul_f32 v[0:1], v[0:1], v[96:97] op_sel_hi:[1,0]
	v_pk_mul_f32 v[16:17], v[16:17], v[96:97] op_sel_hi:[1,0]
	v_pk_mul_f32 v[2:3], v[2:3], v[96:97] op_sel_hi:[1,0]
	v_pk_mul_f32 v[18:19], v[18:19], v[96:97] op_sel_hi:[1,0]
	v_pk_mul_f32 v[4:5], v[4:5], v[96:97] op_sel_hi:[1,0]
	v_pk_mul_f32 v[20:21], v[20:21], v[96:97] op_sel_hi:[1,0]
	v_pk_mul_f32 v[6:7], v[6:7], v[96:97] op_sel_hi:[1,0]
	v_pk_mul_f32 v[22:23], v[22:23], v[96:97] op_sel_hi:[1,0]
	v_pk_mul_f32 v[8:9], v[8:9], v[96:97] op_sel_hi:[1,0]
	v_pk_mul_f32 v[24:25], v[24:25], v[96:97] op_sel_hi:[1,0]
	v_pk_mul_f32 v[10:11], v[10:11], v[96:97] op_sel_hi:[1,0]
	v_pk_mul_f32 v[26:27], v[26:27], v[96:97] op_sel_hi:[1,0]
	v_pk_mul_f32 v[12:13], v[12:13], v[96:97] op_sel_hi:[1,0]
	v_pk_mul_f32 v[28:29], v[28:29], v[96:97] op_sel_hi:[1,0]
	v_pk_mul_f32 v[14:15], v[14:15], v[96:97] op_sel_hi:[1,0]
	v_pk_mul_f32 v[30:31], v[30:31], v[96:97] op_sel_hi:[1,0]
.Lp3lz_skip4:
	v_exp_f32_e32 v63, v48
	v_cvt_pk_bf16_f32 v48, v98, v99
	v_cvt_pk_bf16_f32 v49, v148, v149
	v_cvt_pk_bf16_f32 v50, v52, v53
	v_cvt_pk_bf16_f32 v51, v54, v55
	v_fmac_f32_e32 v98, v162, v96
	v_sub_f32_e32 v32, v32, v97
	v_mfma_f32_32x32x16_bf16 v[0:15], v[144:147], v[48:51], v[0:15]
	v_mov_b32_e32 v197, v97
	v_mfma_f32_32x32x16_bf16 v[16:31], v[140:143], v[48:51], v[16:31]
	v_cvt_pk_bf16_f32 v48, v56, v57
	v_cvt_pk_bf16_f32 v49, v58, v59
	v_cvt_pk_bf16_f32 v50, v60, v61
	v_cvt_pk_bf16_f32 v51, v62, v63
	s_nop 1
	v_mfma_f32_32x32x16_bf16 v[0:15], v[132:135], v[48:51], v[0:15]
	v_mfma_f32_32x32x16_bf16 v[16:31], v[136:139], v[48:51], v[16:31]
	v_add_f32_e32 v48, v99, v98
	v_exp_f32_e32 v49, v32
	v_sub_f32_e32 v32, v33, v97
	v_add_f32_e32 v48, v148, v48
	v_exp_f32_e32 v50, v32
	v_sub_f32_e32 v32, v34, v97
	v_add_f32_e32 v48, v149, v48
	v_exp_f32_e32 v51, v32
	v_sub_f32_e32 v32, v35, v97
	v_add_f32_e32 v48, v52, v48
	v_exp_f32_e32 v52, v32
	v_sub_f32_e32 v32, v36, v97
	v_exp_f32_e32 v36, v32
	v_sub_f32_e32 v32, v37, v97
	v_exp_f32_e32 v37, v32
	v_sub_f32_e32 v32, v38, v97
	v_exp_f32_e32 v38, v32
	v_sub_f32_e32 v32, v39, v97
	v_exp_f32_e32 v39, v32
	v_sub_f32_e32 v32, v40, v97
	v_exp_f32_e32 v40, v32
	v_sub_f32_e32 v32, v41, v97
	v_exp_f32_e32 v41, v32
	v_sub_f32_e32 v32, v42, v97
	v_exp_f32_e32 v42, v32
	v_sub_f32_e32 v32, v43, v97
	v_exp_f32_e32 v43, v32
	v_sub_f32_e32 v32, v44, v97
	v_exp_f32_e32 v44, v32
	v_sub_f32_e32 v32, v45, v97
	v_add_f32_e32 v48, v53, v48
	v_exp_f32_e32 v45, v32
	v_sub_f32_e32 v32, v46, v97
	v_add_f32_e32 v48, v54, v48
	v_exp_f32_e32 v46, v32
	v_sub_f32_e32 v32, v47, v97
	v_add_f32_e32 v48, v55, v48
	v_exp_f32_e32 v47, v32
	v_cvt_pk_bf16_f32 v32, v49, v50
	v_cvt_pk_bf16_f32 v33, v51, v52
	v_cvt_pk_bf16_f32 v34, v36, v37
	v_cvt_pk_bf16_f32 v35, v38, v39
	v_add_f32_e32 v48, v56, v48
	v_add_f32_e32 v48, v57, v48
	v_mfma_f32_32x32x16_bf16 v[0:15], v[128:131], v[32:35], v[0:15]
	v_add_f32_e32 v48, v58, v48
	v_add_f32_e32 v48, v59, v48
	v_add_f32_e32 v48, v60, v48
	v_add_f32_e32 v48, v61, v48
	v_add_f32_e32 v48, v62, v48
	v_add_f32_e32 v48, v63, v48
	v_mfma_f32_32x32x16_bf16 v[16:31], v[108:111], v[32:35], v[16:31]
	v_cvt_pk_bf16_f32 v32, v40, v41
	v_cvt_pk_bf16_f32 v33, v42, v43
	v_cvt_pk_bf16_f32 v34, v44, v45
	v_cvt_pk_bf16_f32 v35, v46, v47
	s_nop 1
	v_mfma_f32_32x32x16_bf16 v[0:15], v[104:107], v[32:35], v[0:15]
	v_mfma_f32_32x32x16_bf16 v[16:31], v[100:103], v[32:35], v[16:31]
	v_add_f32_e32 v32, v49, v48
	v_add_f32_e32 v32, v50, v32
	v_add_f32_e32 v32, v51, v32
	v_add_f32_e32 v32, v52, v32
	v_add_f32_e32 v32, v36, v32
	v_add_f32_e32 v32, v37, v32
	v_add_f32_e32 v32, v38, v32
	v_add_f32_e32 v32, v39, v32
	v_add_f32_e32 v32, v40, v32
	v_add_f32_e32 v32, v41, v32
	v_add_f32_e32 v32, v42, v32
	v_add_f32_e32 v32, v43, v32
	v_add_f32_e32 v32, v44, v32
	v_add_f32_e32 v32, v45, v32
	v_add_f32_e32 v32, v46, v32
	v_add_f32_e32 v162, v47, v32
.LBB0_404:
	ds_bpermute_b32 v32, v238, v162
	v_add_u32_e32 v241, 0x100, v241
	v_add_u32_e32 v240, 0x100, v240
	s_waitcnt lgkmcnt(0)
	v_add_f32_e32 v33, v162, v32
	v_div_scale_f32 v34, s[0:1], v33, v33, 1.0
	v_rcp_f32_e32 v35, v34
	v_div_scale_f32 v36, vcc, 1.0, v33, 1.0
	v_lshrrev_b32_e32 v32, 13, v195
	v_fma_f32 v37, -v34, v35, 1.0
	v_fmac_f32_e32 v35, v37, v35
	v_mul_f32_e32 v37, v36, v35
	v_fma_f32 v38, -v34, v37, v36
	v_fmac_f32_e32 v37, v38, v35
	v_fma_f32 v34, -v34, v37, v36
	v_div_fmas_f32 v34, v34, v35, v37
	v_div_fixup_f32 v34, v34, v33, 1.0
	v_mul_f32_e32 v34, 0x41800000, v34
	v_mul_f32_e32 v0, v0, v34
	v_mul_f32_e32 v1, v1, v34
	v_mul_f32_e32 v16, v16, v34
	v_mul_f32_e32 v17, v17, v34
	v_mul_f32_e32 v2, v2, v34
	v_mul_f32_e32 v18, v18, v34
	v_mul_f32_e32 v3, v3, v34
	v_mul_f32_e32 v19, v19, v34
	v_mul_f32_e32 v4, v4, v34
	v_mul_f32_e32 v20, v20, v34
	v_mul_f32_e32 v5, v5, v34
	v_mul_f32_e32 v21, v21, v34
	v_mul_f32_e32 v6, v6, v34
	v_mul_f32_e32 v22, v22, v34
	v_mul_f32_e32 v7, v7, v34
	v_mul_f32_e32 v23, v23, v34
	v_mul_f32_e32 v8, v8, v34
	v_mul_f32_e32 v24, v24, v34
	v_mul_f32_e32 v9, v9, v34
	v_mul_f32_e32 v25, v25, v34
	v_mul_f32_e32 v10, v10, v34
	v_mul_f32_e32 v26, v26, v34
	v_mul_f32_e32 v11, v11, v34
	v_mul_f32_e32 v27, v27, v34
	v_mul_f32_e32 v12, v12, v34
	v_mul_f32_e32 v28, v28, v34
	v_mul_f32_e32 v13, v13, v34
	v_mul_f32_e32 v29, v29, v34
	v_mul_f32_e32 v14, v14, v34
	v_mul_f32_e32 v30, v30, v34
	v_mul_f32_e32 v15, v15, v34
	v_mul_f32_e32 v31, v31, v34
	v_cvt_pk_fp8_f32 v36, v0, v1
	v_cvt_pk_fp8_f32 v36, v2, v3 op_sel:[0,0,1]
	v_cvt_pk_fp8_f32 v37, v4, v5
	v_cvt_pk_fp8_f32 v37, v6, v7 op_sel:[0,0,1]
	v_cvt_pk_fp8_f32 v38, v8, v9
	v_cvt_pk_fp8_f32 v38, v10, v11 op_sel:[0,0,1]
	v_cvt_pk_fp8_f32 v39, v12, v13
	v_cvt_pk_fp8_f32 v39, v14, v15 op_sel:[0,0,1]
	v_cvt_pk_fp8_f32 v40, v16, v17
	v_cvt_pk_fp8_f32 v40, v18, v19 op_sel:[0,0,1]
	v_cvt_pk_fp8_f32 v41, v20, v21
	v_cvt_pk_fp8_f32 v41, v22, v23 op_sel:[0,0,1]
	ds_write2_b32 v231, v36, v37 offset1:2
	ds_write2_b32 v231, v38, v39 offset0:4 offset1:6
	ds_write2_b32 v231, v40, v41 offset0:8 offset1:10
	v_cvt_pk_fp8_f32 v42, v24, v25
	v_cvt_pk_fp8_f32 v42, v26, v27 op_sel:[0,0,1]
	v_cvt_pk_fp8_f32 v43, v28, v29
	v_cvt_pk_fp8_f32 v43, v30, v31 op_sel:[0,0,1]
	v_lshlrev_b32_e32 v0, 13, v196
	v_cndmask_b32_e64 v1, 0, v236, s[80:81]
	v_or3_b32 v0, v0, v1, v194
	ds_bpermute_b32 v13, v239, v0
	ds_write2_b32 v231, v42, v43 offset0:12 offset1:14
	s_waitcnt lgkmcnt(0)
	v_mov_b32_e32 v14, s19
	v_log_f32_e32 v33, v33
	s_waitcnt lgkmcnt(1)
	v_lshrrev_b32_e32 v8, 13, v13
	v_and_b32_e32 v11, 3, v8
	v_lshlrev_b32_e32 v162, 25, v11
	v_and_b32_e32 v10, 0x1fff, v13
	v_lshl_add_u64 v[8:9], s[28:29], 0, v[162:163]
	v_cmp_eq_u32_e32 vcc, 3, v11
	v_mov_b32_e32 v11, s18
	v_or_b32_e32 v10, s10, v10
	v_cndmask_b32_e32 v8, v8, v11, vcc
	v_mov_b32_e32 v11, s11
	ds_read_b128 v[0:3], v237
	ds_read_b128 v[4:7], v237 offset:16
	v_cndmask_b32_e32 v9, v9, v14, vcc
	v_lshlrev_b64 v[10:11], 10, v[10:11]
	v_lshl_add_u64 v[8:9], v[8:9], 0, v[10:11]
	v_lshl_add_u64 v[8:9], v[8:9], 0, s[72:73]
	v_and_b32_e32 v10, 0x8000, v13
	v_lshl_add_u64 v[8:9], v[8:9], 0, v[172:173]
	v_cmp_eq_u32_e32 vcc, 0, v10
	v_add_f32_e32 v12, v197, v33
	v_mov_b32_e32 v197, v163
	v_cndmask_b32_e32 v9, v9, v175, vcc
	v_cndmask_b32_e32 v8, v8, v174, vcc
	s_waitcnt lgkmcnt(1)
	global_store_dwordx4 v[8:9], v[0:3], off nt
	s_waitcnt lgkmcnt(0)
	global_store_dwordx4 v[8:9], v[4:7], off offset:16 nt
	v_ashrrev_i32_e32 v195, 31, v194
	v_lshlrev_b64 v[0:1], 15, v[196:197]
	v_lshl_add_u64 v[0:1], v[0:1], 0, s[10:11]
	v_lshl_add_u64 v[0:1], v[0:1], 0, v[194:195]
	v_lshlrev_b64 v[0:1], 6, v[0:1]
	v_lshl_add_u64 v[0:1], s[76:77], 0, v[0:1]
	v_cndmask_b32_e64 v1, v177, v1, s[80:81]
	v_cndmask_b32_e64 v0, v176, v0, s[80:81]
	s_and_b64 vcc, exec, s[84:85]
	global_store_dword v[0:1], v12, off
	s_cbranch_vccnz .LBB0_407
	s_waitcnt vmcnt(6)
	v_mov_b64_e32 v[108:109], v[124:125]
	s_waitcnt vmcnt(5)
	v_mov_b64_e32 v[104:105], v[120:121]
	s_waitcnt vmcnt(4)
	v_mov_b64_e32 v[100:101], v[116:117]
	s_waitcnt vmcnt(3)
	v_mov_b64_e32 v[96:97], v[112:113]
	s_mov_b64 s[80:81], s[82:83]
	v_mov_b64_e32 v[110:111], v[126:127]
	v_mov_b64_e32 v[106:107], v[122:123]
	v_mov_b64_e32 v[102:103], v[118:119]
	v_mov_b64_e32 v[98:99], v[114:115]
	v_mov_b32_e32 v196, v32
	v_mov_b32_e32 v194, v242
	s_mov_b32 s58, s8
	v_mov_b32_e32 v195, v243
	s_mov_b64 s[82:83], s[86:87]
	s_branch .LBB0_387
